# mixer conv_part loop: all 13 loads issued before the first consumer (one counted wait instead of three early waits)
# speedup vs baseline: 1.0033x; 1.0033x over previous
; template <bool SAMPLE>
; __device__ __forceinline__ void conv_part(const Params& P, int l, int b, int c, int tid2_, int it_begin, int it_end, int nthr) {
;     ...
;     for (int it = it_begin + tid2; it < it_end; it += nthr) {
;         const int o = it & 31, i = it >> 5, ch = 8 * o;
;         const int tpos = SAMPLE ? i : (c * 64 + i);
;         const bf16_t* zr = Z + (size_t)(row0 + i) * DIN;
;         float bg[8], u[3][8];
;         unpack8(*(const bf16x8*)(zr + 1536 + ch), bg);
; #pragma unroll
;         for (int k = 0; k < 3; ++k) {
;             const bool ok = tpos - k >= 0;
;             const bf16_t* zp = zr - (size_t)(ok ? k : 0) * DIN;
;             float cg[8], hc[8]; unpack8(*(const bf16x8*)(zp + 1792 + ch), cg); unpack8(*(const bf16x8*)(zp + 2048 + ch), hc);
;             float hz[8];
;             if (SAMPLE) unpack8(*(const bf16x8*)(HZC + (ok ? 0 : (2 + tpos - k)) * 256 + ch), hz);
; #pragma unroll
;             for (int e = 0; e < 8; ++e) u[2 - k][e] = ok ? cg[e] * hc[e] : (SAMPLE ? hz[e] : 0.f);
.LBB0_843:
	v_ashrrev_i32_e32 v14, 5, v52
	v_and_b32_e32 v4, 0xf8, v56
	v_add_u32_e32 v48, s37, v14
	v_mov_b64_e32 v[2:3], s[82:83]
	v_mad_i64_i32 v[2:3], s[0:1], v48, s66, v[2:3]
	v_lshlrev_b32_e32 v0, 1, v4
	v_lshl_add_u64 v[12:13], v[2:3], 0, v[0:1]
	v_lshlrev_b32_e32 v50, 2, v4
	global_load_dwordx4 v[44:47], v50, s[42:43]
	global_load_dwordx4 v[40:43], v50, s[42:43] offset:1024
	global_load_dwordx4 v[4:7], v[12:13], off offset:3072
	global_load_dwordx4 v[8:11], v[12:13], off offset:3584
	v_add_co_u32_e32 v12, vcc, s71, v12
	v_add_u32_e32 v51, s36, v14
	s_nop 0
	v_addc_co_u32_e32 v13, vcc, 0, v13, vcc
	v_cmp_gt_i32_e32 vcc, 1, v51
	global_load_dwordx4 v[58:61], v[12:13], off
	s_nop 1
	v_cndmask_b32_e64 v13, -1, 0, vcc
	v_cndmask_b32_e64 v12, v214, 0, vcc
	v_lshl_add_u64 v[12:13], v[2:3], 0, v[12:13]
	v_lshl_add_u64 v[12:13], v[12:13], 0, v[0:1]
	global_load_dwordx4 v[16:19], v[12:13], off offset:3584
	v_add_co_u32_e64 v12, s[0:1], s71, v12
	s_nop 1
	v_addc_co_u32_e64 v13, s[0:1], 0, v13, s[0:1]
	v_cmp_gt_i32_e64 s[0:1], 2, v51
	s_nop 2
	v_cndmask_b32_e64 v15, -1, 0, s[0:1]
	v_cndmask_b32_e64 v14, v215, 0, s[0:1]
	v_lshl_add_u64 v[2:3], v[2:3], 0, v[14:15]
	v_lshl_add_u64 v[2:3], v[2:3], 0, v[0:1]
	global_load_dwordx4 v[20:23], v[12:13], off
	global_load_dwordx4 v[32:35], v[2:3], off offset:3584
	v_add_co_u32_e64 v2, s[2:3], s71, v2
	s_nop 0
	s_nop 0
	v_addc_co_u32_e64 v3, s[2:3], 0, v3, s[2:3]
	global_load_dwordx4 v[36:39], v[2:3], off
	global_load_dwordx4 v[62:65], v50, s[42:43] offset:2048
	global_load_dwordx4 v[28:31], v50, s[42:43] offset:16
	global_load_dwordx4 v[24:27], v50, s[42:43] offset:1040
	global_load_dwordx4 v[12:15], v50, s[42:43] offset:2064
	s_waitcnt vmcnt(10)
	v_mov_b32_e32 v66, v44
	v_mov_b32_e32 v67, v40
	v_lshlrev_b32_e32 v40, 16, v4
	v_and_b32_e32 v49, 0xffff0000, v4
	v_lshlrev_b32_e32 v57, 16, v5
	v_and_b32_e32 v72, 0xffff0000, v5
	s_waitcnt vmcnt(9)
	v_lshlrev_b32_e32 v2, 16, v8
	v_and_b32_e32 v3, 0xffff0000, v8
	v_lshlrev_b32_e32 v4, 16, v9
	v_and_b32_e32 v5, 0xffff0000, v9
	v_lshlrev_b32_e32 v68, 16, v10
	v_and_b32_e32 v69, 0xffff0000, v10
	v_lshlrev_b32_e32 v70, 16, v11
	v_and_b32_e32 v71, 0xffff0000, v11
	s_waitcnt vmcnt(8)
	v_lshlrev_b32_e32 v8, 16, v58
	v_and_b32_e32 v9, 0xffff0000, v58
	v_lshlrev_b32_e32 v10, 16, v59
	v_and_b32_e32 v11, 0xffff0000, v59
	v_lshlrev_b32_e32 v58, 16, v60
	v_and_b32_e32 v59, 0xffff0000, v60
	v_lshlrev_b32_e32 v60, 16, v61
	v_and_b32_e32 v61, 0xffff0000, v61
	v_pk_mul_f32 v[10:11], v[4:5], v[10:11]
	v_pk_mul_f32 v[4:5], v[70:71], v[60:61]
	v_pk_mul_f32 v[8:9], v[2:3], v[8:9]
	v_cmp_gt_i32_e64 s[2:3], 0, v51
	v_pk_mul_f32 v[2:3], v[68:69], v[58:59]
	s_waitcnt vmcnt(7)
	v_lshlrev_b32_e32 v61, 16, v16
	v_cndmask_b32_e64 v44, v8, 0, s[2:3]
	v_cndmask_b32_e64 v73, v9, 0, s[2:3]
	v_cndmask_b32_e64 v74, v10, 0, s[2:3]
	v_cndmask_b32_e64 v75, v11, 0, s[2:3]
	v_lshlrev_b32_e32 v59, 16, v19
	v_and_b32_e32 v19, 0xffff0000, v19
	s_waitcnt vmcnt(6)
	v_lshlrev_b32_e32 v71, 16, v20
	s_waitcnt vmcnt(5)
	v_lshlrev_b32_e32 v60, 16, v32
	v_lshlrev_b32_e32 v58, 16, v35
	s_waitcnt vmcnt(4)
	v_lshlrev_b32_e32 v70, 16, v36
	v_pk_mul_f32 v[60:61], v[60:61], v[70:71]
	v_lshlrev_b32_e32 v69, 16, v23
	v_cndmask_b32_e64 v61, v61, 0, vcc
	v_cndmask_b32_e64 v60, v60, 0, s[0:1]
	v_pk_mul_f32 v[60:61], v[66:67], v[60:61]
	v_lshlrev_b32_e32 v68, 16, v39
	v_add_f32_e32 v60, v61, v60
	s_waitcnt vmcnt(3)
; template <bool SAMPLE>
; __device__ __forceinline__ void conv_part(const Params& P, int l, int b, int c, int tid2_, int it_begin, int it_end, int nthr) {
;     ...
;             for (int e = 0; e < 8; ++e) u[2 - k][e] = ok ? cg[e] * hc[e] : (SAMPLE ? hz[e] : 0.f);
;         }
;         float y[8], ssq = 0.f;
; #pragma unroll
;         for (int e = 0; e < 8; ++e) { y[e] = bg[e] * (cw[ch + e] * u[0][e] + cw[256 + ch + e] * u[1][e] + cw[512 + ch + e] * u[2][e]); ssq += y[e] * y[e]; }
;         ssq += __shfl_xor(ssq, 1); ssq += __shfl_xor(ssq, 2); ssq += __shfl_xor(ssq, 4);
;         const float rn = __builtin_amdgcn_rsqf(ssq * (1.0f / 64.0f) + EPS);
; #pragma unroll
;         for (int e = 0; e < 8; ++e) y[e] *= rn;
;         *(bf16x8*)(MIX + (size_t)(row0 + i) * D + 512 + ch) = pack8(y);
;         if (SAMPLE) { if (i >= 14) store8f(P.out + OFF_CS + ((size_t)(l * 32 + b) * 2 + (i - 14)) * 256 + ch, u[2]); }
;         else { if (tpos >= SEQ - 2) store8f(P.out + OFF_CP + ((size_t)(l * 2 + b) * 2 + (tpos - (SEQ - 2))) * 256 + ch, u[2]); }
;     }
	v_fmac_f32_e32 v60, v44, v62
	v_mul_f32_e32 v62, v60, v40
	v_mov_b32_e32 v40, v45
	v_and_b32_e32 v45, 0xffff0000, v16
	v_and_b32_e32 v44, 0xffff0000, v32
	v_and_b32_e32 v61, 0xffff0000, v20
	v_and_b32_e32 v60, 0xffff0000, v36
	v_pk_mul_f32 v[44:45], v[44:45], v[60:61]
	v_lshlrev_b32_e32 v61, 16, v21
	v_cndmask_b32_e64 v45, v45, 0, vcc
	v_cndmask_b32_e64 v44, v44, 0, s[0:1]
	v_pk_mul_f32 v[40:41], v[40:41], v[44:45]
	v_lshlrev_b32_e32 v45, 16, v17
	v_lshlrev_b32_e32 v44, 16, v33
	v_lshlrev_b32_e32 v60, 16, v37
	v_pk_mul_f32 v[44:45], v[44:45], v[60:61]
	v_add_f32_e32 v16, v40, v41
	v_mov_b32_e32 v40, v46
	v_mov_b32_e32 v41, v42
	v_cndmask_b32_e64 v45, v45, 0, vcc
	v_cndmask_b32_e64 v44, v44, 0, s[0:1]
	v_fmac_f32_e32 v16, v73, v63
	v_pk_mul_f32 v[40:41], v[44:45], v[40:41]
	v_mul_f32_e32 v63, v16, v49
	v_add_f32_e32 v16, v40, v41
	v_fmac_f32_e32 v16, v74, v64
	v_mul_f32_e32 v44, v16, v57
	v_and_b32_e32 v17, 0xffff0000, v17
	v_and_b32_e32 v16, 0xffff0000, v33
	v_and_b32_e32 v21, 0xffff0000, v21
	v_and_b32_e32 v20, 0xffff0000, v37
	v_pk_mul_f32 v[16:17], v[16:17], v[20:21]
	v_lshlrev_b32_e32 v32, 16, v18
	v_and_b32_e32 v33, 0xffff0000, v18
	v_lshlrev_b32_e32 v36, 16, v22
	v_and_b32_e32 v37, 0xffff0000, v22
	v_mov_b32_e32 v42, v47
	v_cndmask_b32_e64 v17, v17, 0, vcc
	v_cndmask_b32_e64 v16, v16, 0, s[0:1]
	v_pk_mul_f32 v[32:33], v[32:33], v[36:37]
	v_lshlrev_b32_e32 v36, 16, v34
	v_and_b32_e32 v37, 0xffff0000, v34
	v_lshlrev_b32_e32 v40, 16, v38
	v_and_b32_e32 v41, 0xffff0000, v38
	v_pk_mul_f32 v[16:17], v[16:17], v[42:43]
	v_cndmask_b32_e64 v33, v33, 0, vcc
	v_cndmask_b32_e64 v32, v32, 0, vcc
	v_pk_mul_f32 v[36:37], v[36:37], v[40:41]
	v_add_f32_e32 v16, v16, v17
	v_cndmask_b32_e64 v37, v37, 0, s[0:1]
	v_cndmask_b32_e64 v36, v36, 0, s[0:1]
	s_waitcnt vmcnt(1)
	v_pk_mul_f32 v[24:25], v[32:33], v[24:25]
	v_mul_f32_e32 v49, v63, v63
	v_fmac_f32_e32 v16, v75, v65
	v_cndmask_b32_e64 v21, v3, 0, s[2:3]
	v_cndmask_b32_e64 v20, v2, 0, s[2:3]
	v_pk_fma_f32 v[24:25], v[36:37], v[28:29], v[24:25]
	v_fmac_f32_e32 v49, v62, v62
	v_mul_f32_e32 v42, v16, v72
	v_lshlrev_b32_e32 v16, 16, v6
	v_and_b32_e32 v17, 0xffff0000, v6
	s_waitcnt vmcnt(0)
	v_pk_fma_f32 v[12:13], v[20:21], v[12:13], v[24:25]
	v_fmac_f32_e32 v49, v44, v44
	v_pk_mul_f32 v[12:13], v[12:13], v[16:17]
	v_fmac_f32_e32 v49, v42, v42
	v_pk_mul_f32 v[16:17], v[12:13], v[12:13]
	v_and_b32_e32 v18, 0xffff0000, v35
	v_and_b32_e32 v21, 0xffff0000, v23
	v_and_b32_e32 v20, 0xffff0000, v39
	v_pk_mul_f32 v[58:59], v[58:59], v[68:69]
	v_add_f32_e32 v6, v49, v16
	v_pk_mul_f32 v[18:19], v[18:19], v[20:21]
	v_cndmask_b32_e64 v59, v59, 0, vcc
	v_cndmask_b32_e64 v58, v58, 0, s[0:1]
	v_add_f32_e32 v24, v6, v17
	v_mov_b32_e32 v16, v30
	v_mov_b32_e32 v17, v26
	v_cndmask_b32_e64 v19, v19, 0, vcc
	v_cndmask_b32_e64 v18, v18, 0, s[0:1]
	v_mov_b32_e32 v26, v31
	v_pk_mul_f32 v[16:17], v[58:59], v[16:17]
	v_pk_mul_f32 v[18:19], v[18:19], v[26:27]
	v_mov_b32_e32 v22, v16
	v_mov_b32_e32 v23, v18
	v_mov_b32_e32 v18, v17
	v_cndmask_b32_e64 v21, v5, 0, s[2:3]
	v_cndmask_b32_e64 v20, v4, 0, s[2:3]
	v_pk_add_f32 v[16:17], v[22:23], v[18:19]
	v_lshlrev_b32_e32 v6, 16, v7
	v_and_b32_e32 v7, 0xffff0000, v7
	v_pk_fma_f32 v[14:15], v[20:21], v[14:15], v[16:17]
	v_ashrrev_i32_e32 v49, 31, v48
	v_pk_mul_f32 v[6:7], v[14:15], v[6:7]
	s_movk_i32 s0, 0x1ffd
	v_pk_mul_f32 v[14:15], v[6:7], v[6:7]
	s_nop 0
	v_add_f32_e32 v14, v24, v14
	v_add_f32_e32 v14, v14, v15
	ds_bpermute_b32 v15, v53, v14
	s_waitcnt lgkmcnt(0)
	v_add_f32_e32 v14, v14, v15
	ds_bpermute_b32 v15, v54, v14
	s_waitcnt lgkmcnt(0)
	v_add_f32_e32 v14, v14, v15
	ds_bpermute_b32 v15, v55, v14
	s_waitcnt lgkmcnt(0)
	v_add_f32_e32 v14, v14, v15
	v_fmamk_f32 v14, v14, 0x3c800000, v209
	v_rsq_f32_e32 v14, v14
	s_nop 0
	v_mul_f32_e32 v15, v62, v14
	v_mul_f32_e32 v6, v6, v14
	v_mul_f32_e32 v7, v7, v14
	v_mul_f32_e32 v16, v63, v14
	v_mul_f32_e32 v19, v12, v14
	v_cvt_pk_bf16_f32 v12, v15, v16
	v_cvt_pk_bf16_f32 v15, v6, v7
	v_lshlrev_b64 v[6:7], 11, v[48:49]
	v_lshl_add_u64 v[6:7], s[94:95], 0, v[6:7]
	v_lshl_add_u64 v[6:7], v[6:7], 0, v[0:1]
	v_add_co_u32_e32 v6, vcc, 0x11300000, v6
	v_mul_f32_e32 v17, v44, v14
	s_nop 0
	v_addc_co_u32_e32 v7, vcc, 0, v7, vcc
	v_cmp_lt_i32_e32 vcc, s0, v51
	v_mul_f32_e32 v18, v42, v14
	v_mul_f32_e32 v20, v13, v14
	v_cvt_pk_bf16_f32 v13, v17, v18
	v_cvt_pk_bf16_f32 v14, v19, v20
	global_store_dwordx4 v[6:7], v[12:15], off offset:1024
	s_and_saveexec_b64 s[0:1], vcc
	s_cbranch_execz .LBB0_842
	v_add_u32_e32 v0, 0xffffe002, v51
	v_lshlrev_b64 v[6:7], 10, v[0:1]
	v_lshl_add_u64 v[6:7], s[6:7], 0, v[6:7]
	v_mov_b32_e32 v51, v1
	v_lshl_add_u64 v[6:7], v[6:7], 0, v[50:51]
	global_store_dwordx4 v[6:7], v[8:11], off
	global_store_dwordx4 v[6:7], v[2:5], off offset:16
	s_branch .LBB0_842
